# NSA2 selected+window loops: near-tile bias/mask via extended LDS table with immediate-offset reads (replaces per-element cmp/min/cndmask index math)
# speedup vs baseline: 1.0338x; 1.0338x over previous
.LBB0_631:
	s_or_b64 exec, exec, s[4:5]
	v_mov_b32_e32 v242, v200
	v_cmp_gt_u32_e32 vcc, 1408, v242
	s_and_saveexec_b64 s[90:91], vcc
	v_cmp_lt_u32_e32 vcc, 703, v242
	v_mov_b32_e32 v252, 0xf149f2ca
	s_nop 0
	v_cndmask_b32_e64 v243, 0, 1, vcc
	v_mul_u32_u24_e32 v244, 704, v243
	v_sub_u32_e32 v244, v242, v244
	v_subrev_u32_e32 v246, 96, v244
	v_max_i32_e32 v247, 0, v246
	v_min_i32_e32 v247, 0x80, v247
	v_lshlrev_b32_e32 v247, 2, v247
	v_add_u32_e32 v247, 0x20004, v247
	ds_read_b32 v247, v247
	v_mul_u32_u24_e32 v251, 0xb00, v243
	v_lshl_add_u32 v251, v244, 2, v251
	v_add_u32_e32 v251, 0x1d000, v251
	s_waitcnt lgkmcnt(0)
	v_mul_lo_u32 v247, v247, 12
	v_add3_u32 v248, v247, v243, s81
	v_ashrrev_i32_e32 v249, 31, v248
	v_lshl_add_u64 v[248:249], v[248:249], 2, s[56:57]
	global_load_dword v250, v[248:249], off
	v_mov_b32_e32 v253, 0x1ff
	v_cmp_gt_u32_e32 vcc, v246, v253
	s_waitcnt vmcnt(0)
	v_mul_f32_e32 v250, 0x41000000, v250
	s_nop 0
	v_cndmask_b32_e32 v250, v250, v252, vcc
	ds_write_b32 v251, v250
	s_or_b64 exec, exec, s[90:91]
	v_add_u32_e32 v242, 512, v200
	v_cmp_gt_u32_e32 vcc, 1408, v242
	s_and_saveexec_b64 s[90:91], vcc
	v_cmp_lt_u32_e32 vcc, 703, v242
	v_mov_b32_e32 v252, 0xf149f2ca
	s_nop 0
	v_cndmask_b32_e64 v243, 0, 1, vcc
	v_mul_u32_u24_e32 v244, 704, v243
	v_sub_u32_e32 v244, v242, v244
	v_subrev_u32_e32 v246, 96, v244
	v_max_i32_e32 v247, 0, v246
	v_min_i32_e32 v247, 0x80, v247
	v_lshlrev_b32_e32 v247, 2, v247
	v_add_u32_e32 v247, 0x20004, v247
	ds_read_b32 v247, v247
	v_mul_u32_u24_e32 v251, 0xb00, v243
	v_lshl_add_u32 v251, v244, 2, v251
	v_add_u32_e32 v251, 0x1d000, v251
	s_waitcnt lgkmcnt(0)
	v_mul_lo_u32 v247, v247, 12
	v_add3_u32 v248, v247, v243, s81
	v_ashrrev_i32_e32 v249, 31, v248
	v_lshl_add_u64 v[248:249], v[248:249], 2, s[56:57]
	global_load_dword v250, v[248:249], off
	v_mov_b32_e32 v253, 0x1ff
	v_cmp_gt_u32_e32 vcc, v246, v253
	s_waitcnt vmcnt(0)
	v_mul_f32_e32 v250, 0x41000000, v250
	s_nop 0
	v_cndmask_b32_e32 v250, v250, v252, vcc
	ds_write_b32 v251, v250
	s_or_b64 exec, exec, s[90:91]
	v_add_u32_e32 v242, 1024, v200
	v_cmp_gt_u32_e32 vcc, 1408, v242
	s_and_saveexec_b64 s[90:91], vcc
	v_cmp_lt_u32_e32 vcc, 703, v242
	v_mov_b32_e32 v252, 0xf149f2ca
	s_nop 0
	v_cndmask_b32_e64 v243, 0, 1, vcc
	v_mul_u32_u24_e32 v244, 704, v243
	v_sub_u32_e32 v244, v242, v244
	v_subrev_u32_e32 v246, 96, v244
	v_max_i32_e32 v247, 0, v246
	v_min_i32_e32 v247, 0x80, v247
	v_lshlrev_b32_e32 v247, 2, v247
	v_add_u32_e32 v247, 0x20004, v247
	ds_read_b32 v247, v247
	v_mul_u32_u24_e32 v251, 0xb00, v243
	v_lshl_add_u32 v251, v244, 2, v251
	v_add_u32_e32 v251, 0x1d000, v251
	s_waitcnt lgkmcnt(0)
	v_mul_lo_u32 v247, v247, 12
	v_add3_u32 v248, v247, v243, s81
	v_ashrrev_i32_e32 v249, 31, v248
	v_lshl_add_u64 v[248:249], v[248:249], 2, s[56:57]
	global_load_dword v250, v[248:249], off
	v_mov_b32_e32 v253, 0x1ff
	v_cmp_gt_u32_e32 vcc, v246, v253
	s_waitcnt vmcnt(0)
	v_mul_f32_e32 v250, 0x41000000, v250
	s_nop 0
	v_cndmask_b32_e32 v250, v250, v252, vcc
	ds_write_b32 v251, v250
	s_or_b64 exec, exec, s[90:91]
	v_readfirstlane_b32 s92, v200
	s_lshr_b32 s92, s92, 8
	s_and_b32 s92, s92, 1
	s_mul_i32 s93, s92, 0xb00
	s_add_i32 s93, s93, 0x1d000
	s_add_i32 s92, s93, 148
	s_add_i32 s94, s93, 276
	s_add_i32 s95, s93, 192
	s_add_i32 s96, s93, 320
	s_xor_b64 s[50:51], s[2:3], -1
	s_and_b64 s[0:1], s[2:3], exec
	s_cselect_b32 s61, s82, s80
	s_lshl_b32 s60, s61, 8
	v_and_b32_e32 v181, 0xc0, v2
	v_and_b32_e32 v151, 31, v2
	v_or_b32_e32 v182, s60, v181
	v_ashrrev_i32_e32 v3, 8, v2
	v_or_b32_e32 v0, v182, v151
	v_add_u32_e32 v185, s81, v3
	v_lshl_add_u64 v[146:147], s[34:35], 0, v[0:1]
	v_mad_u64_u32 v[4:5], s[0:1], v146, s73, v[138:139]
	v_lshlrev_b32_e32 v152, 6, v185
	v_bfe_u32 v186, v2, 5, 1
	v_mad_i32_i24 v5, v147, s73, v5
	v_ashrrev_i32_e32 v153, 31, v152
	v_ashrrev_i32_e32 v183, 3, v2
	v_lshl_add_u64 v[4:5], v[152:153], 1, v[4:5]
	v_lshlrev_b32_e32 v0, 4, v186
	v_med3_i32 v36, v183, 0, v141
	v_lshlrev_b32_e32 v38, 3, v2
	v_lshl_add_u64 v[24:25], v[4:5], 0, v[0:1]
	v_mul_u32_u24_e32 v36, 0x600, v36
	v_mov_b32_e32 v37, v1
	v_and_b32_e32 v150, 56, v38
	v_add_co_u32_e32 v28, vcc, s74, v24
	v_lshl_add_u64 v[36:37], v[36:37], 1, s[44:45]
	v_lshlrev_b32_e32 v44, 1, v150
	v_mov_b32_e32 v45, v1
	v_lshl_add_u64 v[32:33], v[24:25], 0, s[20:21]
	v_addc_co_u32_e32 v29, vcc, 0, v25, vcc
	v_lshl_add_u64 v[40:41], v[36:37], 0, v[44:45]
	global_load_dwordx4 v[4:7], v[24:25], off
	global_load_dwordx4 v[8:11], v[24:25], off offset:32
	global_load_dwordx4 v[12:15], v[32:33], off offset:32
	global_load_dwordx4 v[16:19], v[32:33], off offset:64
	global_load_dwordx4 v[20:23], v[24:25], off offset:64
	s_nop 0
	global_load_dwordx4 v[24:27], v[24:25], off offset:96
	s_nop 0
	global_load_dwordx4 v[28:31], v[28:29], off
	s_nop 0
	global_load_dwordx4 v[32:35], v[32:33], off offset:96
	s_nop 0
	global_load_dwordx4 v[36:39], v[40:41], off offset:1792
	s_nop 0
	global_load_dwordx4 v[40:43], v[40:41], off offset:1920
	v_or_b32_e32 v148, 32, v146
	v_mov_b32_e32 v149, v147
	v_lshl_add_u64 v[46:47], v[146:147], 2, s[18:19]
	v_lshl_add_u64 v[48:49], v[148:149], 2, s[18:19]
	global_load_dword v187, v[46:47], off
	global_load_dword v188, v[48:49], off
	v_lshlrev_b32_e32 v47, 7, v2
	v_and_b32_e32 v46, 63, v2
	v_lshlrev_b32_e32 v48, 4, v2
	v_mad_i32_i24 v175, v3, s72, 0
	v_and_b32_e32 v3, 0xffffe000, v47
	v_lshlrev_b32_e32 v46, 4, v46
	v_mul_lo_u32 v47, v183, s75
	v_and_b32_e32 v48, 0x70, v48
	v_add_u32_e32 v3, 0, v3
	v_and_b32_e32 v49, 16, v2
	v_lshrrev_b32_e32 v50, 2, v2
	v_mul_u32_u24_e32 v51, 0x90, v151
	v_add3_u32 v140, 0, v47, v48
	v_add_u32_e32 v176, v3, v46
	v_lshlrev_b32_e32 v184, 2, v186
	v_lshlrev_b32_e32 v3, 2, v2
	v_mad_u64_u32 v[142:143], s[0:1], v183, 48, v[140:141]
	v_add3_u32 v178, 0, v51, v0
	v_and_or_b32 v0, v50, 3, v184
	v_and_or_b32 v3, v3, 12, v49
	v_mul_u32_u24_e32 v0, 0xc0, v0
	v_lshlrev_b32_e32 v3, 1, v3
	v_add3_u32 v179, 0, v0, v3
	v_bitop3_b32 v0, v2, 31, v170 bitop3:0xe0
	s_lshl_b32 s84, s61, 2
	v_lshl_add_u64 v[144:145], s[44:45], 0, v[44:45]
	v_mad_u64_u32 v[154:155], s[0:1], v146, s73, 0
	v_sub_u32_e32 v192, v0, v184
	v_mov_b32_e32 v0, v1
	v_mov_b32_e32 v2, v1
	v_mov_b32_e32 v3, v1
	s_mov_b32 s85, 0
	s_add_i32 s83, s84, 4
	v_or_b32_e32 v143, 31, v182
	v_or_b32_e32 v177, 63, v182
	v_mad_i32_i24 v155, v147, s73, v155
	v_add_u32_e32 v190, 0xffffff41, v182
	v_add_u32_e32 v191, 0xffffff61, v182
	v_add_u32_e32 v180, 64, v183
	s_add_i32 s86, s60, 0x100
	v_mov_b32_e32 v193, 0xf149f2ca
	v_mov_b32_e32 v194, 0xf149f2ca
	s_mov_b32 s87, 0
	s_mov_b32 s0, 0
	v_mov_b64_e32 v[156:157], v[0:1]
	s_waitcnt vmcnt(11)
	ds_write_b128 v176, v[4:7] offset:53248
	s_waitcnt vmcnt(10)
	ds_write_b128 v176, v[8:11] offset:54272
	s_waitcnt vmcnt(7)
	ds_write_b128 v176, v[20:23] offset:55296
	s_waitcnt vmcnt(6)
	ds_write_b128 v176, v[24:27] offset:56320
	s_waitcnt vmcnt(5)
	ds_write_b128 v176, v[28:31] offset:57344
	ds_write_b128 v176, v[12:15] offset:58368
	ds_write_b128 v176, v[16:19] offset:59392
	s_waitcnt vmcnt(4)
	ds_write_b128 v176, v[32:35] offset:60416
	s_waitcnt lgkmcnt(0)
	s_barrier
	s_waitcnt vmcnt(3)
	ds_write_b128 v140, v[36:39]
	s_waitcnt vmcnt(2)
	ds_write_b128 v142, v[40:43] offset:18432
	s_waitcnt lgkmcnt(0)
	s_barrier
	ds_read_b32 v189, v175 offset:43524
	v_mov_b32_e32 v16, v1
	v_mov_b32_e32 v17, v1
	v_mov_b32_e32 v4, v1
	v_mov_b32_e32 v5, v1
	v_mov_b32_e32 v6, v1
	v_mov_b32_e32 v7, v1
	v_mov_b32_e32 v8, v1
	v_mov_b32_e32 v9, v1
	v_mov_b32_e32 v10, v1
	v_mov_b32_e32 v11, v1
	v_mov_b32_e32 v12, v1
	v_mov_b32_e32 v13, v1
	v_mov_b32_e32 v14, v1
	v_mov_b32_e32 v15, v1
	v_mov_b64_e32 v[48:49], v[16:17]
	v_mov_b64_e32 v[64:65], v[16:17]
	v_mov_b64_e32 v[32:33], v[16:17]
	v_mov_b64_e32 v[46:47], v[14:15]
	v_mov_b64_e32 v[44:45], v[12:13]
	v_mov_b64_e32 v[42:43], v[10:11]
	v_mov_b64_e32 v[40:41], v[8:9]
	v_mov_b64_e32 v[38:39], v[6:7]
	v_mov_b64_e32 v[36:37], v[4:5]
	v_mov_b64_e32 v[34:35], v[2:3]
	v_mov_b64_e32 v[62:63], v[14:15]
	v_mov_b64_e32 v[60:61], v[12:13]
	v_mov_b64_e32 v[58:59], v[10:11]
	v_mov_b64_e32 v[56:57], v[8:9]
	v_mov_b64_e32 v[54:55], v[6:7]
	v_mov_b64_e32 v[52:53], v[4:5]
	v_mov_b64_e32 v[50:51], v[2:3]
	v_mov_b64_e32 v[30:31], v[14:15]
	v_mov_b64_e32 v[28:29], v[12:13]
	v_mov_b64_e32 v[26:27], v[10:11]
	v_mov_b64_e32 v[24:25], v[8:9]
	v_mov_b64_e32 v[22:23], v[6:7]
	v_mov_b64_e32 v[20:21], v[4:5]
	v_mov_b64_e32 v[18:19], v[2:3]

.LBB0_634:
	s_lshl_b32 s0, 1, s0
	s_waitcnt vmcnt(1)
	v_and_b32_e32 v0, s0, v187
	v_mov_b32_e32 v167, 0
	v_cmp_ne_u32_e64 s[6:7], 0, v0
	v_cmp_le_u32_e32 vcc, s85, v143
	v_mov_b32_e32 v0, 0
	s_and_saveexec_b64 s[2:3], vcc
	v_cndmask_b32_e64 v0, 0, 1, s[6:7]
	v_cmp_ne_u32_e32 vcc, 0, v0
	s_cmp_lg_u64 vcc, 0
	s_cselect_b64 s[4:5], -1, 0
	v_cndmask_b32_e64 v0, 0, 1, s[4:5]
	s_or_b64 exec, exec, s[2:3]
	s_waitcnt vmcnt(0)
	v_and_b32_e32 v66, s0, v188
	v_cmp_ne_u32_e32 vcc, 0, v66
	v_cmp_le_u32_e64 s[2:3], s85, v177
	s_and_saveexec_b64 s[4:5], s[2:3]
	v_cndmask_b32_e64 v66, 0, 1, vcc
	v_cmp_ne_u32_e64 s[2:3], 0, v66
	s_cmp_lg_u64 s[2:3], 0
	s_cselect_b64 s[0:1], -1, 0
	v_cndmask_b32_e64 v167, 0, 1, s[0:1]
	s_or_b64 exec, exec, s[4:5]
	v_and_b32_e32 v66, 1, v0
	v_cmp_eq_u32_e64 s[8:9], 1, v66
	v_and_b32_e32 v66, 1, v167
	v_cmp_eq_u32_e64 s[2:3], 1, v66
	s_or_b64 s[0:1], s[8:9], s[2:3]
	s_and_saveexec_b64 s[54:55], s[0:1]
	s_cbranch_execz .LBB0_646
	s_cmp_eq_u32 s87, 0
	s_cselect_b64 s[58:59], -1, 0
	s_and_b64 s[0:1], s[58:59], exec
	s_cselect_b32 s0, 0, 0x2400
	v_add_u32_e32 v168, s0, v178
	ds_read_b128 v[158:161], v168
	ds_read_b128 v[162:165], v176 offset:53248
	v_cmp_gt_i32_e64 s[4:5], s85, v190
	s_waitcnt lgkmcnt(2)
	v_cndmask_b32_e64 v66, v173, v189, s[6:7]
	ds_read_b128 v[196:199], v168 offset:32
	ds_read_b128 v[202:205], v176 offset:54272
	ds_read_b128 v[206:209], v176 offset:57344
	ds_read_b128 v[210:213], v176 offset:58368
	v_cndmask_b32_e64 v166, 0, v171, s[4:5]
	v_cndmask_b32_e64 v66, v66, 0, s[4:5]
	v_cndmask_b32_e32 v67, v173, v189, vcc
	v_cmp_gt_i32_e64 s[4:5], s85, v191
	v_cndmask_b32_e64 v82, v173, v66, s[8:9]
	v_mov_b32_e32 v83, v82
	v_cndmask_b32_e64 v67, v67, 0, s[4:5]
	v_cndmask_b32_e64 v66, v173, v67, s[2:3]
	v_mov_b32_e32 v84, v82
	v_mov_b32_e32 v85, v82
	v_mov_b32_e32 v86, v82
	v_mov_b32_e32 v87, v82
	v_mov_b32_e32 v88, v82
	v_mov_b32_e32 v89, v82
	v_mov_b32_e32 v90, v82
	v_mov_b32_e32 v91, v82
	v_mov_b32_e32 v92, v82
	v_mov_b32_e32 v93, v82
	v_mov_b32_e32 v94, v82
	v_mov_b32_e32 v95, v82
	v_mov_b32_e32 v96, v82
	v_mov_b32_e32 v97, v82
	v_mov_b32_e32 v67, v66
	v_mov_b32_e32 v68, v66
	v_mov_b32_e32 v69, v66
	v_mov_b32_e32 v70, v66
	v_mov_b32_e32 v71, v66
	v_mov_b32_e32 v72, v66
	v_mov_b32_e32 v73, v66
	v_mov_b32_e32 v74, v66
	v_mov_b32_e32 v75, v66
	v_mov_b32_e32 v76, v66
	v_mov_b32_e32 v77, v66
	v_mov_b32_e32 v78, v66
	v_mov_b32_e32 v79, v66
	v_mov_b32_e32 v80, v66
	v_mov_b32_e32 v81, v66
	s_waitcnt lgkmcnt(4)
	v_mfma_f32_32x32x16_bf16 v[98:113], v[158:161], v[162:165], v[82:97]
	s_waitcnt lgkmcnt(1)
	v_mfma_f32_32x32x16_bf16 v[114:129], v[158:161], v[206:209], v[66:81]
	ds_read_b128 v[158:161], v168 offset:4608
	ds_read_b128 v[214:217], v168 offset:4640
	s_waitcnt lgkmcnt(1)
	v_mfma_f32_32x32x16_bf16 v[82:97], v[158:161], v[162:165], v[82:97]
	v_mfma_f32_32x32x16_bf16 v[66:81], v[158:161], v[206:209], v[66:81]
	v_mfma_f32_32x32x16_bf16 v[98:113], v[196:199], v[202:205], v[98:113]
	v_mfma_f32_32x32x16_bf16 v[114:129], v[196:199], v[210:213], v[114:129]
	ds_read_b128 v[158:161], v168 offset:64
	ds_read_b128 v[162:165], v176 offset:55296
	ds_read_b128 v[196:199], v168 offset:96
	ds_read_b128 v[206:209], v176 offset:56320
	s_waitcnt lgkmcnt(4)
	v_mfma_f32_32x32x16_bf16 v[82:97], v[214:217], v[202:205], v[82:97]
	v_mfma_f32_32x32x16_bf16 v[66:81], v[214:217], v[210:213], v[66:81]
	ds_read_b128 v[202:205], v176 offset:59392
	ds_read_b128 v[210:213], v176 offset:60416
	s_waitcnt lgkmcnt(4)
	v_mfma_f32_32x32x16_bf16 v[98:113], v[158:161], v[162:165], v[98:113]
	s_waitcnt lgkmcnt(1)
	v_mfma_f32_32x32x16_bf16 v[114:129], v[158:161], v[202:205], v[114:129]
	ds_read_b128 v[158:161], v168 offset:4672
	ds_read_b128 v[214:217], v168 offset:4704
	s_waitcnt lgkmcnt(1)
	v_mfma_f32_32x32x16_bf16 v[82:97], v[158:161], v[162:165], v[82:97]
	v_mfma_f32_32x32x16_bf16 v[66:81], v[158:161], v[202:205], v[66:81]
	v_cndmask_b32_e64 v158, 0, v172, s[6:7]
	v_or3_b32 v0, v158, v166, v0
	v_cndmask_b32_e64 v158, v158, v0, s[8:9]
	v_and_b32_e32 v0, 0x100, v158
	v_cmp_ne_u32_e64 s[6:7], 0, v0
	v_add_u32_e32 v0, s60, v192
	v_min_i32_e32 v204, 0x80, v0
	v_mfma_f32_32x32x16_bf16 v[98:113], v[196:199], v[206:209], v[98:113]
	v_add_u32_e32 v203, -1, v0
	v_add_u32_e32 v202, -2, v0
	v_add_u32_e32 v201, -3, v0
	v_add_u32_e32 v195, -16, v0
	v_subrev_u32_e32 v169, 17, v0
	v_subrev_u32_e32 v168, 18, v0
	v_subrev_u32_e32 v166, 19, v0
	v_mfma_f32_32x32x16_bf16 v[114:129], v[196:199], v[210:213], v[114:129]
	v_add_u32_e32 v199, -8, v0
	v_add_u32_e32 v198, -9, v0
	v_add_u32_e32 v197, -10, v0
	v_add_u32_e32 v196, -11, v0
	v_subrev_u32_e32 v165, 24, v0
	v_subrev_u32_e32 v164, 25, v0
	v_subrev_u32_e32 v163, 26, v0
	s_waitcnt lgkmcnt(0)
	v_mfma_f32_32x32x16_bf16 v[82:97], v[214:217], v[206:209], v[82:97]
	v_subrev_u32_e32 v162, 27, v0
	v_mfma_f32_32x32x16_bf16 v[66:81], v[214:217], v[210:213], v[66:81]
	s_and_saveexec_b64 s[8:9], s[6:7]
	s_cbranch_execz .LBB0_641
	v_lshl_add_u32 v206, v0, 2, s92
	v_and_b32_e32 v205, 0x10000, v158
	v_cmp_ne_u32_e64 s[6:7], 0, v205
	v_mov_b32_e32 v207, s93
	s_nop 1
	v_cndmask_b32_e64 v206, v207, v206, s[6:7]
	ds_read_b32 v208, v206 offset:236
	ds_read_b32 v209, v206 offset:232
	ds_read_b32 v210, v206 offset:228
	ds_read_b32 v211, v206 offset:224
	ds_read_b32 v212, v206 offset:204
	ds_read_b32 v213, v206 offset:200
	ds_read_b32 v214, v206 offset:196
	ds_read_b32 v215, v206 offset:192
	ds_read_b32 v216, v206 offset:172
	ds_read_b32 v217, v206 offset:168
	ds_read_b32 v218, v206 offset:164
	ds_read_b32 v219, v206 offset:160
	ds_read_b32 v220, v206 offset:140
	ds_read_b32 v221, v206 offset:136
	ds_read_b32 v222, v206 offset:132
	ds_read_b32 v223, v206 offset:128
	ds_read_b32 v224, v206 offset:108
	ds_read_b32 v225, v206 offset:104
	ds_read_b32 v226, v206 offset:100
	ds_read_b32 v227, v206 offset:96
	ds_read_b32 v228, v206 offset:76
	ds_read_b32 v229, v206 offset:72
	ds_read_b32 v230, v206 offset:68
	ds_read_b32 v231, v206 offset:64
	ds_read_b32 v232, v206 offset:44
	ds_read_b32 v233, v206 offset:40
	ds_read_b32 v234, v206 offset:36
	ds_read_b32 v235, v206 offset:32
	ds_read_b32 v236, v206 offset:12
	ds_read_b32 v237, v206 offset:8
	ds_read_b32 v238, v206 offset:4
	ds_read_b32 v239, v206 offset:0
	s_waitcnt lgkmcnt(14)
	v_pk_add_f32 v[98:99], v[98:99], v[208:209]
	v_pk_add_f32 v[100:101], v[100:101], v[210:211]
	v_pk_add_f32 v[102:103], v[102:103], v[212:213]
	v_pk_add_f32 v[104:105], v[104:105], v[214:215]
	v_pk_add_f32 v[106:107], v[106:107], v[216:217]
	v_pk_add_f32 v[108:109], v[108:109], v[218:219]
	v_pk_add_f32 v[110:111], v[110:111], v[220:221]
	v_pk_add_f32 v[112:113], v[112:113], v[222:223]
	s_waitcnt lgkmcnt(0)
	v_pk_add_f32 v[82:83], v[82:83], v[224:225]
	v_pk_add_f32 v[84:85], v[84:85], v[226:227]
	v_pk_add_f32 v[86:87], v[86:87], v[228:229]
	v_pk_add_f32 v[88:89], v[88:89], v[230:231]
	v_pk_add_f32 v[90:91], v[90:91], v[232:233]
	v_pk_add_f32 v[92:93], v[92:93], v[234:235]
	v_pk_add_f32 v[94:95], v[94:95], v[236:237]
	v_pk_add_f32 v[96:97], v[96:97], v[238:239]
.LBB0_641:
	s_or_b64 exec, exec, s[8:9]
	v_cndmask_b32_e32 v158, 0, v172, vcc
	v_cndmask_b32_e64 v159, 0, v171, s[4:5]
	v_or3_b32 v159, v158, v159, v167
	v_cndmask_b32_e64 v158, v158, v159, s[2:3]
	v_and_b32_e32 v159, 0x100, v158
	v_cmp_ne_u32_e32 vcc, 0, v159
	s_and_saveexec_b64 s[2:3], vcc
	s_cbranch_execz .LBB0_643
	v_lshl_add_u32 v206, v0, 2, s94
	v_and_b32_e32 v205, 0x10000, v158
	v_cmp_ne_u32_e32 vcc, 0, v205
	v_mov_b32_e32 v207, s93
	s_nop 1
	v_cndmask_b32_e32 v206, v207, v206, vcc
	ds_read_b32 v208, v206 offset:236
	ds_read_b32 v209, v206 offset:232
	ds_read_b32 v210, v206 offset:228
	ds_read_b32 v211, v206 offset:224
	ds_read_b32 v212, v206 offset:204
	ds_read_b32 v213, v206 offset:200
	ds_read_b32 v214, v206 offset:196
	ds_read_b32 v215, v206 offset:192
	ds_read_b32 v216, v206 offset:172
	ds_read_b32 v217, v206 offset:168
	ds_read_b32 v218, v206 offset:164
	ds_read_b32 v219, v206 offset:160
	ds_read_b32 v220, v206 offset:140
	ds_read_b32 v221, v206 offset:136
	ds_read_b32 v222, v206 offset:132
	ds_read_b32 v223, v206 offset:128
	ds_read_b32 v224, v206 offset:108
	ds_read_b32 v225, v206 offset:104
	ds_read_b32 v226, v206 offset:100
	ds_read_b32 v227, v206 offset:96
	ds_read_b32 v228, v206 offset:76
	ds_read_b32 v229, v206 offset:72
	ds_read_b32 v230, v206 offset:68
	ds_read_b32 v231, v206 offset:64
	ds_read_b32 v232, v206 offset:44
	ds_read_b32 v233, v206 offset:40
	ds_read_b32 v234, v206 offset:36
	ds_read_b32 v235, v206 offset:32
	ds_read_b32 v236, v206 offset:12
	ds_read_b32 v237, v206 offset:8
	ds_read_b32 v238, v206 offset:4
	ds_read_b32 v239, v206 offset:0
	s_waitcnt lgkmcnt(14)
	v_pk_add_f32 v[114:115], v[114:115], v[208:209]
	v_pk_add_f32 v[116:117], v[116:117], v[210:211]
	v_pk_add_f32 v[118:119], v[118:119], v[212:213]
	v_pk_add_f32 v[120:121], v[120:121], v[214:215]
	v_pk_add_f32 v[122:123], v[122:123], v[216:217]
	v_pk_add_f32 v[124:125], v[124:125], v[218:219]
	v_pk_add_f32 v[126:127], v[126:127], v[220:221]
	v_pk_add_f32 v[128:129], v[128:129], v[222:223]
	s_waitcnt lgkmcnt(0)
	v_pk_add_f32 v[66:67], v[66:67], v[224:225]
	v_pk_add_f32 v[68:69], v[68:69], v[226:227]
	v_pk_add_f32 v[70:71], v[70:71], v[228:229]
	v_pk_add_f32 v[72:73], v[72:73], v[230:231]
	v_pk_add_f32 v[74:75], v[74:75], v[232:233]
	v_pk_add_f32 v[76:77], v[76:77], v[234:235]
	v_pk_add_f32 v[78:79], v[78:79], v[236:237]
	v_pk_add_f32 v[80:81], v[80:81], v[238:239]

.LBB0_655:
	s_add_i32 s0, s84, 63
	v_cmp_le_u32_e32 vcc, s84, v143
	v_cmp_ge_i32_e64 s[2:3], s0, v168
	s_and_b64 s[2:3], vcc, s[2:3]
	v_cmp_le_u32_e32 vcc, s84, v177
	v_cmp_ge_i32_e64 s[4:5], s0, v169
	s_and_b64 vcc, vcc, s[4:5]
	s_or_b64 s[4:5], s[2:3], vcc
	s_and_saveexec_b64 s[60:61], s[4:5]
	s_cbranch_execz .LBB0_663
	v_cmp_gt_i32_e64 s[4:5], s0, v182
	v_cmp_lt_i32_e64 s[6:7], s84, v183
	v_cmp_gt_i32_e64 s[8:9], s0, v167
	v_cmp_lt_i32_e64 s[10:11], s84, v185
	s_or_b64 s[6:7], s[4:5], s[6:7]
	s_or_b64 s[8:9], s[8:9], s[10:11]
	s_cmp_eq_u32 s86, 0
	s_cselect_b64 s[4:5], -1, 0
	s_and_b64 s[0:1], s[4:5], exec
	s_waitcnt lgkmcnt(0)
	v_cndmask_b32_e64 v0, v184, 0, s[6:7]
	v_cndmask_b32_e64 v66, v184, 0, s[8:9]
	s_cselect_b32 s0, 0, 0x2400
	v_cndmask_b32_e64 v82, v173, v66, s[2:3]
	v_cndmask_b32_e32 v66, v173, v0, vcc
	v_add_u32_e32 v0, s0, v178
	ds_read_b128 v[156:159], v0
	ds_read_b128 v[160:163], v176 offset:53248
	ds_read_b128 v[188:191], v0 offset:32
	ds_read_b128 v[192:195], v176 offset:54272
	ds_read_b128 v[196:199], v176 offset:57344
	ds_read_b128 v[202:205], v176 offset:58368
	v_mov_b32_e32 v83, v82
	v_mov_b32_e32 v84, v82
	v_mov_b32_e32 v85, v82
	v_mov_b32_e32 v86, v82
	v_mov_b32_e32 v87, v82
	v_mov_b32_e32 v88, v82
	v_mov_b32_e32 v89, v82
	v_mov_b32_e32 v90, v82
	v_mov_b32_e32 v91, v82
	v_mov_b32_e32 v92, v82
	v_mov_b32_e32 v93, v82
	v_mov_b32_e32 v94, v82
	v_mov_b32_e32 v95, v82
	v_mov_b32_e32 v96, v82
	v_mov_b32_e32 v97, v82
	v_mov_b32_e32 v67, v66
	v_mov_b32_e32 v68, v66
	v_mov_b32_e32 v69, v66
	v_mov_b32_e32 v70, v66
	v_mov_b32_e32 v71, v66
	v_mov_b32_e32 v72, v66
	v_mov_b32_e32 v73, v66
	v_mov_b32_e32 v74, v66
	v_mov_b32_e32 v75, v66
	v_mov_b32_e32 v76, v66
	v_mov_b32_e32 v77, v66
	v_mov_b32_e32 v78, v66
	v_mov_b32_e32 v79, v66
	v_mov_b32_e32 v80, v66
	v_mov_b32_e32 v81, v66
	s_waitcnt lgkmcnt(4)
	v_mfma_f32_32x32x16_bf16 v[98:113], v[156:159], v[160:163], v[82:97]
	v_add_u32_e32 v165, -8, v181
	s_and_b64 s[0:1], s[2:3], s[8:9]
	s_waitcnt lgkmcnt(1)
	v_mfma_f32_32x32x16_bf16 v[114:129], v[156:159], v[196:199], v[66:81]
	ds_read_b128 v[156:159], v0 offset:4608
	ds_read_b128 v[206:209], v0 offset:4640
	s_waitcnt lgkmcnt(1)
	v_mfma_f32_32x32x16_bf16 v[82:97], v[156:159], v[160:163], v[82:97]
	v_mfma_f32_32x32x16_bf16 v[66:81], v[156:159], v[196:199], v[66:81]
	ds_read_b128 v[156:159], v0 offset:64
	ds_read_b128 v[160:163], v176 offset:55296
	ds_read_b128 v[212:215], v0 offset:96
	ds_read_b128 v[216:219], v176 offset:56320
	v_add_u32_e32 v199, 3, v181
	v_add_u32_e32 v197, 2, v181
	v_min_i32_e32 v201, 0x80, v197
	v_mfma_f32_32x32x16_bf16 v[98:113], v[188:191], v[192:195], v[98:113]
	v_mfma_f32_32x32x16_bf16 v[114:129], v[188:191], v[202:205], v[114:129]
	ds_read_b128 v[188:191], v176 offset:59392
	ds_read_b128 v[220:223], v176 offset:60416
	s_waitcnt lgkmcnt(6)
	v_mfma_f32_32x32x16_bf16 v[82:97], v[206:209], v[192:195], v[82:97]
	v_add_u32_e32 v195, 1, v181
	v_add_u32_e32 v192, -5, v181
	v_min_i32_e32 v198, 0x80, v195
	v_min_i32_e32 v194, 0x80, v192
	v_mfma_f32_32x32x16_bf16 v[66:81], v[206:209], v[202:205], v[66:81]
	v_add_u32_e32 v208, 11, v181
	v_add_u32_e32 v206, 10, v181
	v_add_u32_e32 v204, 9, v181
	v_add_u32_e32 v203, 8, v181
	v_min_i32_e32 v210, 0x80, v208
	v_min_i32_e32 v209, 0x80, v206
	v_min_i32_e32 v207, 0x80, v204
	s_waitcnt lgkmcnt(4)
	v_mfma_f32_32x32x16_bf16 v[98:113], v[156:159], v[160:163], v[98:113]
	v_min_i32_e32 v205, 0x80, v203
	v_min_i32_e32 v202, 0x80, v199
	s_waitcnt lgkmcnt(1)
	v_mfma_f32_32x32x16_bf16 v[114:129], v[156:159], v[188:191], v[114:129]
	ds_read_b128 v[156:159], v0 offset:4672
	ds_read_b128 v[224:227], v0 offset:4704
	v_add_u32_e32 v0, -16, v181
	s_waitcnt lgkmcnt(1)
	v_mfma_f32_32x32x16_bf16 v[82:97], v[156:159], v[160:163], v[82:97]
	v_add_u32_e32 v162, -13, v181
	v_add_u32_e32 v160, -14, v181
	v_min_i32_e32 v164, 0x80, v162
	v_min_i32_e32 v163, 0x80, v160
	v_mfma_f32_32x32x16_bf16 v[66:81], v[156:159], v[188:191], v[66:81]
	v_min_i32_e32 v156, 0x80, v181
	v_add_u32_e32 v190, -6, v181
	v_add_u32_e32 v188, -7, v181
	v_add_u32_e32 v158, -15, v181
	v_add_u32_e32 v196, 1, v156
	v_min_i32_e32 v193, 0x80, v190
	v_min_i32_e32 v191, 0x80, v188
	v_mfma_f32_32x32x16_bf16 v[98:113], v[212:215], v[216:219], v[98:113]
	v_min_i32_e32 v189, 0x80, v165
	v_min_i32_e32 v161, 0x80, v158
	v_min_i32_e32 v159, 0x80, v0
	v_mfma_f32_32x32x16_bf16 v[114:129], v[212:215], v[220:223], v[114:129]
	s_waitcnt lgkmcnt(0)
	v_mfma_f32_32x32x16_bf16 v[82:97], v[224:227], v[216:219], v[82:97]
	v_mfma_f32_32x32x16_bf16 v[66:81], v[224:227], v[220:223], v[66:81]
	s_and_saveexec_b64 s[8:9], s[0:1]
	s_cbranch_execz .LBB0_658
	v_lshl_add_u32 v211, v181, 2, s95
	ds_read_b32 v212, v211 offset:236
	ds_read_b32 v213, v211 offset:232
	ds_read_b32 v214, v211 offset:228
	ds_read_b32 v215, v211 offset:224
	ds_read_b32 v216, v211 offset:204
	ds_read_b32 v217, v211 offset:200
	ds_read_b32 v218, v211 offset:196
	ds_read_b32 v219, v211 offset:192
	ds_read_b32 v220, v211 offset:172
	ds_read_b32 v221, v211 offset:168
	ds_read_b32 v222, v211 offset:164
	ds_read_b32 v223, v211 offset:160
	ds_read_b32 v224, v211 offset:140
	ds_read_b32 v225, v211 offset:136
	ds_read_b32 v226, v211 offset:132
	ds_read_b32 v227, v211 offset:128
	ds_read_b32 v228, v211 offset:108
	ds_read_b32 v229, v211 offset:104
	ds_read_b32 v230, v211 offset:100
	ds_read_b32 v231, v211 offset:96
	ds_read_b32 v232, v211 offset:76
	ds_read_b32 v233, v211 offset:72
	ds_read_b32 v234, v211 offset:68
	ds_read_b32 v235, v211 offset:64
	ds_read_b32 v236, v211 offset:44
	ds_read_b32 v237, v211 offset:40
	ds_read_b32 v238, v211 offset:36
	ds_read_b32 v239, v211 offset:32
	ds_read_b32 v240, v211 offset:12
	ds_read_b32 v241, v211 offset:8
	ds_read_b32 v242, v211 offset:4
	ds_read_b32 v243, v211 offset:0
	s_waitcnt lgkmcnt(14)
	v_pk_add_f32 v[98:99], v[98:99], v[212:213]
	v_pk_add_f32 v[100:101], v[100:101], v[214:215]
	v_pk_add_f32 v[102:103], v[102:103], v[216:217]
	v_pk_add_f32 v[104:105], v[104:105], v[218:219]
	v_pk_add_f32 v[106:107], v[106:107], v[220:221]
	v_pk_add_f32 v[108:109], v[108:109], v[222:223]
	v_pk_add_f32 v[110:111], v[110:111], v[224:225]
	v_pk_add_f32 v[112:113], v[112:113], v[226:227]
	s_waitcnt lgkmcnt(0)
	v_pk_add_f32 v[82:83], v[82:83], v[228:229]
	v_pk_add_f32 v[84:85], v[84:85], v[230:231]
	v_pk_add_f32 v[86:87], v[86:87], v[232:233]
	v_pk_add_f32 v[88:89], v[88:89], v[234:235]
	v_pk_add_f32 v[90:91], v[90:91], v[236:237]
	v_pk_add_f32 v[92:93], v[92:93], v[238:239]
	v_pk_add_f32 v[94:95], v[94:95], v[240:241]
	v_pk_add_f32 v[96:97], v[96:97], v[242:243]
.LBB0_658:
	s_or_b64 exec, exec, s[8:9]
	s_and_b64 s[0:1], vcc, s[6:7]
	s_and_saveexec_b64 s[2:3], s[0:1]
	s_cbranch_execz .LBB0_660
	v_lshl_add_u32 v211, v181, 2, s96
	ds_read_b32 v212, v211 offset:236
	ds_read_b32 v213, v211 offset:232
	ds_read_b32 v214, v211 offset:228
	ds_read_b32 v215, v211 offset:224
	ds_read_b32 v216, v211 offset:204
	ds_read_b32 v217, v211 offset:200
	ds_read_b32 v218, v211 offset:196
	ds_read_b32 v219, v211 offset:192
	ds_read_b32 v220, v211 offset:172
	ds_read_b32 v221, v211 offset:168
	ds_read_b32 v222, v211 offset:164
	ds_read_b32 v223, v211 offset:160
	ds_read_b32 v224, v211 offset:140
	ds_read_b32 v225, v211 offset:136
	ds_read_b32 v226, v211 offset:132
	ds_read_b32 v227, v211 offset:128
	ds_read_b32 v228, v211 offset:108
	ds_read_b32 v229, v211 offset:104
	ds_read_b32 v230, v211 offset:100
	ds_read_b32 v231, v211 offset:96
	ds_read_b32 v232, v211 offset:76
	ds_read_b32 v233, v211 offset:72
	ds_read_b32 v234, v211 offset:68
	ds_read_b32 v235, v211 offset:64
	ds_read_b32 v236, v211 offset:44
	ds_read_b32 v237, v211 offset:40
	ds_read_b32 v238, v211 offset:36
	ds_read_b32 v239, v211 offset:32
	ds_read_b32 v240, v211 offset:12
	ds_read_b32 v241, v211 offset:8
	ds_read_b32 v242, v211 offset:4
	ds_read_b32 v243, v211 offset:0
	s_waitcnt lgkmcnt(14)
	v_pk_add_f32 v[114:115], v[114:115], v[212:213]
	v_pk_add_f32 v[116:117], v[116:117], v[214:215]
	v_pk_add_f32 v[118:119], v[118:119], v[216:217]
	v_pk_add_f32 v[120:121], v[120:121], v[218:219]
	v_pk_add_f32 v[122:123], v[122:123], v[220:221]
	v_pk_add_f32 v[124:125], v[124:125], v[222:223]
	v_pk_add_f32 v[126:127], v[126:127], v[224:225]
	v_pk_add_f32 v[128:129], v[128:129], v[226:227]
	s_waitcnt lgkmcnt(0)
	v_pk_add_f32 v[66:67], v[66:67], v[228:229]
	v_pk_add_f32 v[68:69], v[68:69], v[230:231]
	v_pk_add_f32 v[70:71], v[70:71], v[232:233]
	v_pk_add_f32 v[72:73], v[72:73], v[234:235]
	v_pk_add_f32 v[74:75], v[74:75], v[236:237]
	v_pk_add_f32 v[76:77], v[76:77], v[238:239]
	v_pk_add_f32 v[78:79], v[78:79], v[240:241]
	v_pk_add_f32 v[80:81], v[80:81], v[242:243]
